# residual GEMM epilogues (out = base + gate*acc, f32) rewritten with 8 loads per wave in flight instead of one
# speedup vs baseline: 1.1662x; 1.0096x over previous
;     DEV void operator()(const Acc& acc, const Unit& u, int wr, int wc, int fr, int fq, LAS unsigned char*) const {
;     ...
;         const int col0 = u.pn * 256 + wc * 32 + 4 * fq; const float* gp = gate + (size_t)mr * 6144 + col0;
;         f32x4 gv[2][2];
; #pragma unroll
;         for (int bj = 0; bj < 2; ++bj)
; #pragma unroll
;             for (int n = 0; n < 2; ++n) gv[bj][n] = *(const f32x4*)(gp + bj * 128 + n * 16);
; #pragma unroll
;         for (int ai = 0; ai < 2; ++ai)
; #pragma unroll
;             for (int m = 0; m < 4; ++m) { const size_t off = (size_t)(ai * 128 + wr * 64 + m * 16 + fr) * DM + col0;
; #pragma unroll
;                 for (int bj = 0; bj < 2; ++bj)
; #pragma unroll
;                     for (int n = 0; n < 2; ++n) { const f32x4 bs = *(const f32x4*)(bp + off + bj * 128 + n * 16);
;                         *(f32x4*)(op + off + bj * 128 + n * 16) = bs + gv[bj][n] * acc[ai][bj][m][n]; }
;                 if (m & 1) asm volatile("" ::: "memory"); }
.LBB0_523:
	s_lshl_b32 s19, s68, 8
	s_min_i32 s21, s68, 0x80
	s_ashr_i32 s21, s21, 4
	s_add_i32 s23, s19, 0xffff8000
	s_ashr_i32 s30, s19, 31
	s_cmpk_lt_i32 s68, 0x80
	v_readlane_b32 s34, v250, 21
	s_cselect_b32 s31, s30, 0
	s_cselect_b32 s30, s19, s23
	v_readlane_b32 s35, v250, 22
	s_cselect_b32 s19, s53, s55
	s_cselect_b32 s23, s52, s54
	s_cselect_b32 s68, s35, s51
	s_cselect_b32 s70, s34, s50
	s_lshl_b64 s[30:31], s[30:31], 12
	s_add_u32 s34, s23, s30
	s_addc_u32 s35, s19, s31
	s_add_u32 s30, s70, s30
	v_mov_b32_e32 v132, v166
	v_mov_b32_e32 v130, v159
	s_addc_u32 s31, s68, s31
	s_lshl_b32 s19, s61, 8
	s_or_b32 s19, s19, s56
	v_add_u32_e32 v164, s49, v132
	v_lshl_add_u32 v162, v130, 2, s19
	v_ashrrev_i32_e32 v165, 31, v164
	s_mul_hi_i32 s19, s21, 0x6000
	s_mulk_i32 s21, 0x6000
	v_readlane_b32 s70, v249, 21
	v_ashrrev_i32_e32 v163, 31, v162
	v_lshlrev_b64 v[132:133], 10, v[164:165]
	v_readlane_b32 s71, v249, 22
	s_add_u32 s70, s70, s21
	v_lshl_add_u64 v[132:133], v[132:133], 0, v[162:163]
	s_addc_u32 s71, s71, s19
	v_lshlrev_b64 v[174:175], 2, v[132:133]
	v_lshl_add_u64 v[130:131], v[162:163], 2, s[70:71]
	v_lshl_add_u64 v[176:177], s[34:35], 0, v[174:175]
	global_load_dwordx4 v[142:145], v[130:131], off
	global_load_dwordx4 v[138:141], v[130:131], off offset:64
	global_load_dwordx4 v[134:137], v[130:131], off offset:512
	s_nop 0
	global_load_dwordx4 v[130:133], v[130:131], off offset:576
	global_load_dwordx4 v[162:165], v174, s[34:35]
	global_load_dwordx4 v[170:173], v174, s[34:35] offset:64
	global_load_dwordx4 v[192:195], v174, s[34:35] offset:512
	global_load_dwordx4 v[196:199], v174, s[34:35] offset:576
	v_add_u32_e32 v176, 0x10000, v174
	global_load_dwordx4 v[200:203], v176, s[34:35]
	global_load_dwordx4 v[204:207], v176, s[34:35] offset:64
	global_load_dwordx4 v[208:211], v176, s[34:35] offset:512
	global_load_dwordx4 v[212:215], v176, s[34:35] offset:576
	s_waitcnt vmcnt(4)
	v_fma_f32 v162, v126, v142, v162
	v_fma_f32 v163, v127, v143, v163
	v_fma_f32 v164, v128, v144, v164
	v_fma_f32 v165, v129, v145, v165
	v_fma_f32 v170, v122, v138, v170
	v_fma_f32 v171, v123, v139, v171
	v_fma_f32 v172, v124, v140, v172
	v_fma_f32 v173, v125, v141, v173
	v_fma_f32 v192, v118, v134, v192
	v_fma_f32 v193, v119, v135, v193
	v_fma_f32 v194, v120, v136, v194
	v_fma_f32 v195, v121, v137, v195
	v_fma_f32 v196, v106, v130, v196
	v_fma_f32 v197, v107, v131, v197
	v_fma_f32 v198, v108, v132, v198
	v_fma_f32 v199, v109, v133, v199
	global_store_dwordx4 v174, v[162:165], s[30:31]
	global_store_dwordx4 v174, v[170:173], s[30:31] offset:64
	global_store_dwordx4 v174, v[192:195], s[30:31] offset:512
	global_store_dwordx4 v174, v[196:199], s[30:31] offset:576
	v_add_u32_e32 v176, 0x20000, v174
	global_load_dwordx4 v[126:129], v176, s[34:35]
	global_load_dwordx4 v[122:125], v176, s[34:35] offset:64
	global_load_dwordx4 v[118:121], v176, s[34:35] offset:512
	global_load_dwordx4 v[106:109], v176, s[34:35] offset:576
	s_waitcnt vmcnt(8)
	v_fma_f32 v200, v114, v142, v200
	v_fma_f32 v201, v115, v143, v201
	v_fma_f32 v202, v116, v144, v202
	v_fma_f32 v203, v117, v145, v203
	v_fma_f32 v204, v110, v138, v204
	v_fma_f32 v205, v111, v139, v205
	v_fma_f32 v206, v112, v140, v206
	v_fma_f32 v207, v113, v141, v207
	v_fma_f32 v208, v102, v134, v208
	v_fma_f32 v209, v103, v135, v209
	v_fma_f32 v210, v104, v136, v210
	v_fma_f32 v211, v105, v137, v211
	v_fma_f32 v212, v90, v130, v212
	v_fma_f32 v213, v91, v131, v213
	v_fma_f32 v214, v92, v132, v214
	v_fma_f32 v215, v93, v133, v215
	v_add_u32_e32 v176, 0x10000, v174
	global_store_dwordx4 v176, v[200:203], s[30:31]
	global_store_dwordx4 v176, v[204:207], s[30:31] offset:64
	global_store_dwordx4 v176, v[208:211], s[30:31] offset:512
	global_store_dwordx4 v176, v[212:215], s[30:31] offset:576
	v_add_u32_e32 v176, 0x30000, v174
	global_load_dwordx4 v[114:117], v176, s[34:35]
	global_load_dwordx4 v[110:113], v176, s[34:35] offset:64
	global_load_dwordx4 v[102:105], v176, s[34:35] offset:512
	global_load_dwordx4 v[90:93], v176, s[34:35] offset:576
	s_waitcnt vmcnt(8)
	v_fma_f32 v126, v98, v142, v126
	v_fma_f32 v127, v99, v143, v127
	v_fma_f32 v128, v100, v144, v128
	v_fma_f32 v129, v101, v145, v129
	v_fma_f32 v122, v94, v138, v122
	v_fma_f32 v123, v95, v139, v123
	v_fma_f32 v124, v96, v140, v124
	v_fma_f32 v125, v97, v141, v125
	v_fma_f32 v118, v86, v134, v118
	v_fma_f32 v119, v87, v135, v119
	v_fma_f32 v120, v88, v136, v120
	v_fma_f32 v121, v89, v137, v121
	v_fma_f32 v106, v74, v130, v106
	v_fma_f32 v107, v75, v131, v107
	v_fma_f32 v108, v76, v132, v108
	v_fma_f32 v109, v77, v133, v109
	v_add_u32_e32 v176, 0x20000, v174
	global_store_dwordx4 v176, v[126:129], s[30:31]
	global_store_dwordx4 v176, v[122:125], s[30:31] offset:64
	global_store_dwordx4 v176, v[118:121], s[30:31] offset:512
	global_store_dwordx4 v176, v[106:109], s[30:31] offset:576
	v_add_u32_e32 v176, 0x80000, v174
	global_load_dwordx4 v[98:101], v176, s[34:35]
	global_load_dwordx4 v[94:97], v176, s[34:35] offset:64
	global_load_dwordx4 v[86:89], v176, s[34:35] offset:512
	global_load_dwordx4 v[74:77], v176, s[34:35] offset:576
	s_waitcnt vmcnt(8)
;     DEV void operator()(const Acc& acc, const Unit& u, int wr, int wc, int fr, int fq, LAS unsigned char*) const {
;     ...
;         for (int ai = 0; ai < 2; ++ai)
; #pragma unroll
;             for (int m = 0; m < 4; ++m) { const size_t off = (size_t)(ai * 128 + wr * 64 + m * 16 + fr) * DM + col0;
; #pragma unroll
;                 for (int bj = 0; bj < 2; ++bj)
; #pragma unroll
;                     for (int n = 0; n < 2; ++n) { const f32x4 bs = *(const f32x4*)(bp + off + bj * 128 + n * 16);
;                         *(f32x4*)(op + off + bj * 128 + n * 16) = bs + gv[bj][n] * acc[ai][bj][m][n]; }
;                 if (m & 1) asm volatile("" ::: "memory"); }
	v_fma_f32 v114, v82, v142, v114
	v_fma_f32 v115, v83, v143, v115
	v_fma_f32 v116, v84, v144, v116
	v_fma_f32 v117, v85, v145, v117
	v_fma_f32 v110, v78, v138, v110
	v_fma_f32 v111, v79, v139, v111
	v_fma_f32 v112, v80, v140, v112
	v_fma_f32 v113, v81, v141, v113
	v_fma_f32 v102, v70, v134, v102
	v_fma_f32 v103, v71, v135, v103
	v_fma_f32 v104, v72, v136, v104
	v_fma_f32 v105, v73, v137, v105
	v_fma_f32 v90, v66, v130, v90
	v_fma_f32 v91, v67, v131, v91
	v_fma_f32 v92, v68, v132, v92
	v_fma_f32 v93, v69, v133, v93
	v_add_u32_e32 v176, 0x30000, v174
	global_store_dwordx4 v176, v[114:117], s[30:31]
	global_store_dwordx4 v176, v[110:113], s[30:31] offset:64
	global_store_dwordx4 v176, v[102:105], s[30:31] offset:512
	global_store_dwordx4 v176, v[90:93], s[30:31] offset:576
	v_add_u32_e32 v176, 0x90000, v174
	global_load_dwordx4 v[82:85], v176, s[34:35]
	global_load_dwordx4 v[78:81], v176, s[34:35] offset:64
	global_load_dwordx4 v[70:73], v176, s[34:35] offset:512
	global_load_dwordx4 v[66:69], v176, s[34:35] offset:576
	s_waitcnt vmcnt(8)
	v_fma_f32 v98, v62, v142, v98
	v_fma_f32 v99, v63, v143, v99
	v_fma_f32 v100, v64, v144, v100
	v_fma_f32 v101, v65, v145, v101
	v_fma_f32 v94, v58, v138, v94
	v_fma_f32 v95, v59, v139, v95
	v_fma_f32 v96, v60, v140, v96
	v_fma_f32 v97, v61, v141, v97
	v_fma_f32 v86, v54, v134, v86
	v_fma_f32 v87, v55, v135, v87
	v_fma_f32 v88, v56, v136, v88
	v_fma_f32 v89, v57, v137, v89
	v_fma_f32 v74, v42, v130, v74
	v_fma_f32 v75, v43, v131, v75
	v_fma_f32 v76, v44, v132, v76
	v_fma_f32 v77, v45, v133, v77
	v_add_u32_e32 v176, 0x80000, v174
	global_store_dwordx4 v176, v[98:101], s[30:31]
	global_store_dwordx4 v176, v[94:97], s[30:31] offset:64
	global_store_dwordx4 v176, v[86:89], s[30:31] offset:512
	global_store_dwordx4 v176, v[74:77], s[30:31] offset:576
	v_add_u32_e32 v176, 0xa0000, v174
	global_load_dwordx4 v[62:65], v176, s[34:35]
	global_load_dwordx4 v[58:61], v176, s[34:35] offset:64
	global_load_dwordx4 v[54:57], v176, s[34:35] offset:512
	global_load_dwordx4 v[42:45], v176, s[34:35] offset:576
	s_waitcnt vmcnt(8)
	v_fma_f32 v82, v50, v142, v82
	v_fma_f32 v83, v51, v143, v83
	v_fma_f32 v84, v52, v144, v84
	v_fma_f32 v85, v53, v145, v85
	v_fma_f32 v78, v46, v138, v78
	v_fma_f32 v79, v47, v139, v79
	v_fma_f32 v80, v48, v140, v80
	v_fma_f32 v81, v49, v141, v81
	v_fma_f32 v70, v38, v134, v70
	v_fma_f32 v71, v39, v135, v71
	v_fma_f32 v72, v40, v136, v72
	v_fma_f32 v73, v41, v137, v73
	v_fma_f32 v66, v26, v130, v66
	v_fma_f32 v67, v27, v131, v67
	v_fma_f32 v68, v28, v132, v68
	v_fma_f32 v69, v29, v133, v69
	v_add_u32_e32 v176, 0x90000, v174
	global_store_dwordx4 v176, v[82:85], s[30:31]
	global_store_dwordx4 v176, v[78:81], s[30:31] offset:64
	global_store_dwordx4 v176, v[70:73], s[30:31] offset:512
	global_store_dwordx4 v176, v[66:69], s[30:31] offset:576
	v_add_u32_e32 v176, 0xb0000, v174
	global_load_dwordx4 v[50:53], v176, s[34:35]
	global_load_dwordx4 v[46:49], v176, s[34:35] offset:64
	global_load_dwordx4 v[38:41], v176, s[34:35] offset:512
	global_load_dwordx4 v[26:29], v176, s[34:35] offset:576
	s_waitcnt vmcnt(8)
	v_fma_f32 v62, v34, v142, v62
	v_fma_f32 v63, v35, v143, v63
	v_fma_f32 v64, v36, v144, v64
	v_fma_f32 v65, v37, v145, v65
	v_fma_f32 v58, v30, v138, v58
	v_fma_f32 v59, v31, v139, v59
	v_fma_f32 v60, v32, v140, v60
	v_fma_f32 v61, v33, v141, v61
	v_fma_f32 v54, v22, v134, v54
	v_fma_f32 v55, v23, v135, v55
	v_fma_f32 v56, v24, v136, v56
	v_fma_f32 v57, v25, v137, v57
	v_fma_f32 v42, v10, v130, v42
	v_fma_f32 v43, v11, v131, v43
	v_fma_f32 v44, v12, v132, v44
	v_fma_f32 v45, v13, v133, v45
	v_add_u32_e32 v176, 0xa0000, v174
	global_store_dwordx4 v176, v[62:65], s[30:31]
	global_store_dwordx4 v176, v[58:61], s[30:31] offset:64
	global_store_dwordx4 v176, v[54:57], s[30:31] offset:512
	global_store_dwordx4 v176, v[42:45], s[30:31] offset:576
	s_waitcnt vmcnt(4)
	v_fma_f32 v50, v18, v142, v50
	v_fma_f32 v51, v19, v143, v51
	v_fma_f32 v52, v20, v144, v52
	v_fma_f32 v53, v21, v145, v53
	v_fma_f32 v46, v14, v138, v46
	v_fma_f32 v47, v15, v139, v47
	v_fma_f32 v48, v16, v140, v48
	v_fma_f32 v49, v17, v141, v49
	v_fma_f32 v38, v6, v134, v38
	v_fma_f32 v39, v7, v135, v39
	v_fma_f32 v40, v8, v136, v40
	v_fma_f32 v41, v9, v137, v41
	v_fma_f32 v26, v2, v130, v26
	v_fma_f32 v27, v3, v131, v27
	v_fma_f32 v28, v4, v132, v28
	v_fma_f32 v29, v5, v133, v29
	v_add_u32_e32 v176, 0xb0000, v174
	global_store_dwordx4 v176, v[50:53], s[30:31]
	global_store_dwordx4 v176, v[46:49], s[30:31] offset:64
	global_store_dwordx4 v176, v[38:41], s[30:31] offset:512
	global_store_dwordx4 v176, v[26:29], s[30:31] offset:576
	s_and_b64 vcc, exec, s[2:3]
	s_mov_b64 s[2:3], -1
	s_cbranch_vccnz .LBB0_505
	s_andn2_b64 vcc, exec, s[12:13]
	s_cbranch_vccnz .LBB0_504
	s_barrier
	s_branch .LBB0_504

;     DEV void operator()(const Acc& acc, const Unit& u, int wr, int wc, int fr, int fq, LAS unsigned char*) const {
;     ...
;         const int rt = u.pm * 256; const bool isx = rt < TX; const int mr = isx ? (rt >> 12) : 8;
;         const float* bp = isx ? baseX + (size_t)rt * DM : baseC + (size_t)(rt - TX) * DM;
;         float* op = isx ? outX + (size_t)rt * DM : outC + (size_t)(rt - TX) * DM;
;         const int col0 = u.pn * 256 + wc * 32 + 4 * fq; const float* gp = gate + (size_t)mr * 6144 + col0;
;         f32x4 gv[2][2];
; #pragma unroll
;         for (int bj = 0; bj < 2; ++bj)
; #pragma unroll
;             for (int n = 0; n < 2; ++n) gv[bj][n] = *(const f32x4*)(gp + bj * 128 + n * 16);
; #pragma unroll
;         for (int ai = 0; ai < 2; ++ai)
; #pragma unroll
;             for (int m = 0; m < 4; ++m) { const size_t off = (size_t)(ai * 128 + wr * 64 + m * 16 + fr) * DM + col0;
; #pragma unroll
;                 for (int bj = 0; bj < 2; ++bj)
; #pragma unroll
;                     for (int n = 0; n < 2; ++n) { const f32x4 bs = *(const f32x4*)(bp + off + bj * 128 + n * 16);
;                         *(f32x4*)(op + off + bj * 128 + n * 16) = bs + gv[bj][n] * acc[ai][bj][m][n]; }
;                 if (m & 1) asm volatile("" ::: "memory"); }
.LBB0_1984:
	s_lshl_b32 s19, s60, 8
	s_min_i32 s21, s60, 0x80
	s_ashr_i32 s21, s21, 4
	s_add_i32 s28, s19, 0xffff8000
	s_ashr_i32 s29, s19, 31
	s_cmpk_lt_i32 s60, 0x80
	s_cselect_b32 s29, s29, 0
	s_cselect_b32 s28, s19, s28
	s_cselect_b32 s19, s55, s51
	s_cselect_b32 s30, s54, s50
	s_cselect_b32 s60, s75, s69
	s_cselect_b32 s61, s74, s68
	s_lshl_b64 s[28:29], s[28:29], 12
	s_add_u32 s30, s30, s28
	s_addc_u32 s31, s19, s29
	s_add_u32 s28, s61, s28
	v_mov_b32_e32 v132, v161
	v_mov_b32_e32 v130, v160
	s_addc_u32 s29, s60, s29
	s_lshl_b32 s19, s57, 8
	s_or_b32 s19, s19, s48
	v_add_u32_e32 v158, s47, v132
	v_lshl_add_u32 v156, v130, 2, s19
	v_ashrrev_i32_e32 v159, 31, v158
	s_mul_hi_i32 s19, s21, 0x6000
	s_mulk_i32 s21, 0x6000
	v_readlane_b32 s60, v249, 26
	v_ashrrev_i32_e32 v157, 31, v156
	v_lshlrev_b64 v[132:133], 10, v[158:159]
	v_readlane_b32 s61, v249, 27
	s_add_u32 s60, s60, s21
	v_lshl_add_u64 v[132:133], v[132:133], 0, v[156:157]
	s_addc_u32 s61, s61, s19
	v_lshlrev_b64 v[168:169], 2, v[132:133]
	v_lshl_add_u64 v[130:131], v[156:157], 2, s[60:61]
	v_lshl_add_u64 v[170:171], s[30:31], 0, v[168:169]
	global_load_dwordx4 v[142:145], v[130:131], off
	global_load_dwordx4 v[138:141], v[130:131], off offset:64
	global_load_dwordx4 v[134:137], v[130:131], off offset:512
	s_nop 0
	global_load_dwordx4 v[130:133], v[130:131], off offset:576
	global_load_dwordx4 v[156:159], v168, s[30:31]
	global_load_dwordx4 v[164:167], v168, s[30:31] offset:64
	global_load_dwordx4 v[174:177], v168, s[30:31] offset:512
	global_load_dwordx4 v[190:193], v168, s[30:31] offset:576
	v_add_u32_e32 v170, 0x10000, v168
	global_load_dwordx4 v[194:197], v170, s[30:31]
	global_load_dwordx4 v[198:201], v170, s[30:31] offset:64
	global_load_dwordx4 v[202:205], v170, s[30:31] offset:512
	global_load_dwordx4 v[206:209], v170, s[30:31] offset:576
	s_waitcnt vmcnt(4)
	v_fma_f32 v156, v126, v142, v156
	v_fma_f32 v157, v127, v143, v157
	v_fma_f32 v158, v128, v144, v158
	v_fma_f32 v159, v129, v145, v159
	v_fma_f32 v164, v122, v138, v164
	v_fma_f32 v165, v123, v139, v165
	v_fma_f32 v166, v124, v140, v166
	v_fma_f32 v167, v125, v141, v167
	v_fma_f32 v174, v118, v134, v174
	v_fma_f32 v175, v119, v135, v175
	v_fma_f32 v176, v120, v136, v176
	v_fma_f32 v177, v121, v137, v177
	v_fma_f32 v190, v106, v130, v190
	v_fma_f32 v191, v107, v131, v191
	v_fma_f32 v192, v108, v132, v192
	v_fma_f32 v193, v109, v133, v193
	global_store_dwordx4 v168, v[156:159], s[28:29]
	global_store_dwordx4 v168, v[164:167], s[28:29] offset:64
	global_store_dwordx4 v168, v[174:177], s[28:29] offset:512
	global_store_dwordx4 v168, v[190:193], s[28:29] offset:576
	v_add_u32_e32 v170, 0x20000, v168
	global_load_dwordx4 v[126:129], v170, s[30:31]
	global_load_dwordx4 v[122:125], v170, s[30:31] offset:64
	global_load_dwordx4 v[118:121], v170, s[30:31] offset:512
	global_load_dwordx4 v[106:109], v170, s[30:31] offset:576
	s_waitcnt vmcnt(8)
	v_fma_f32 v194, v114, v142, v194
	v_fma_f32 v195, v115, v143, v195
	v_fma_f32 v196, v116, v144, v196
	v_fma_f32 v197, v117, v145, v197
	v_fma_f32 v198, v110, v138, v198
	v_fma_f32 v199, v111, v139, v199
	v_fma_f32 v200, v112, v140, v200
	v_fma_f32 v201, v113, v141, v201
	v_fma_f32 v202, v102, v134, v202
	v_fma_f32 v203, v103, v135, v203
	v_fma_f32 v204, v104, v136, v204
	v_fma_f32 v205, v105, v137, v205
	v_fma_f32 v206, v88, v130, v206
	v_fma_f32 v207, v89, v131, v207
	v_fma_f32 v208, v90, v132, v208
	v_fma_f32 v209, v91, v133, v209
	v_add_u32_e32 v170, 0x10000, v168
	global_store_dwordx4 v170, v[194:197], s[28:29]
	global_store_dwordx4 v170, v[198:201], s[28:29] offset:64
	global_store_dwordx4 v170, v[202:205], s[28:29] offset:512
	global_store_dwordx4 v170, v[206:209], s[28:29] offset:576
	v_add_u32_e32 v170, 0x30000, v168
	global_load_dwordx4 v[114:117], v170, s[30:31]
	global_load_dwordx4 v[110:113], v170, s[30:31] offset:64
	global_load_dwordx4 v[102:105], v170, s[30:31] offset:512
	global_load_dwordx4 v[88:91], v170, s[30:31] offset:576
	s_waitcnt vmcnt(8)
	v_fma_f32 v126, v98, v142, v126
	v_fma_f32 v127, v99, v143, v127
	v_fma_f32 v128, v100, v144, v128
	v_fma_f32 v129, v101, v145, v129
	v_fma_f32 v122, v92, v138, v122
	v_fma_f32 v123, v93, v139, v123
	v_fma_f32 v124, v94, v140, v124
	v_fma_f32 v125, v95, v141, v125
	v_fma_f32 v118, v84, v134, v118
	v_fma_f32 v119, v85, v135, v119
	v_fma_f32 v120, v86, v136, v120
	v_fma_f32 v121, v87, v137, v121
	v_fma_f32 v106, v72, v130, v106
	v_fma_f32 v107, v73, v131, v107
	v_fma_f32 v108, v74, v132, v108
	v_fma_f32 v109, v75, v133, v109
	v_add_u32_e32 v170, 0x20000, v168
	global_store_dwordx4 v170, v[126:129], s[28:29]
	global_store_dwordx4 v170, v[122:125], s[28:29] offset:64
	global_store_dwordx4 v170, v[118:121], s[28:29] offset:512
	global_store_dwordx4 v170, v[106:109], s[28:29] offset:576
	v_add_u32_e32 v170, 0x80000, v168
	global_load_dwordx4 v[98:101], v170, s[30:31]
	global_load_dwordx4 v[92:95], v170, s[30:31] offset:64
	global_load_dwordx4 v[84:87], v170, s[30:31] offset:512
	global_load_dwordx4 v[72:75], v170, s[30:31] offset:576
	s_waitcnt vmcnt(8)
;     DEV void operator()(const Acc& acc, const Unit& u, int wr, int wc, int fr, int fq, LAS unsigned char*) const {
;     ...
;         for (int ai = 0; ai < 2; ++ai)
; #pragma unroll
;             for (int m = 0; m < 4; ++m) { const size_t off = (size_t)(ai * 128 + wr * 64 + m * 16 + fr) * DM + col0;
; #pragma unroll
;                 for (int bj = 0; bj < 2; ++bj)
; #pragma unroll
;                     for (int n = 0; n < 2; ++n) { const f32x4 bs = *(const f32x4*)(bp + off + bj * 128 + n * 16);
;                         *(f32x4*)(op + off + bj * 128 + n * 16) = bs + gv[bj][n] * acc[ai][bj][m][n]; }
;                 if (m & 1) asm volatile("" ::: "memory"); }
	v_fma_f32 v114, v80, v142, v114
	v_fma_f32 v115, v81, v143, v115
	v_fma_f32 v116, v82, v144, v116
	v_fma_f32 v117, v83, v145, v117
	v_fma_f32 v110, v76, v138, v110
	v_fma_f32 v111, v77, v139, v111
	v_fma_f32 v112, v78, v140, v112
	v_fma_f32 v113, v79, v141, v113
	v_fma_f32 v102, v68, v134, v102
	v_fma_f32 v103, v69, v135, v103
	v_fma_f32 v104, v70, v136, v104
	v_fma_f32 v105, v71, v137, v105
	v_fma_f32 v88, v64, v130, v88
	v_fma_f32 v89, v65, v131, v89
	v_fma_f32 v90, v66, v132, v90
	v_fma_f32 v91, v67, v133, v91
	v_add_u32_e32 v170, 0x30000, v168
	global_store_dwordx4 v170, v[114:117], s[28:29]
	global_store_dwordx4 v170, v[110:113], s[28:29] offset:64
	global_store_dwordx4 v170, v[102:105], s[28:29] offset:512
	global_store_dwordx4 v170, v[88:91], s[28:29] offset:576
	v_add_u32_e32 v170, 0x90000, v168
	global_load_dwordx4 v[80:83], v170, s[30:31]
	global_load_dwordx4 v[76:79], v170, s[30:31] offset:64
	global_load_dwordx4 v[68:71], v170, s[30:31] offset:512
	global_load_dwordx4 v[64:67], v170, s[30:31] offset:576
	s_waitcnt vmcnt(8)
	v_fma_f32 v98, v60, v142, v98
	v_fma_f32 v99, v61, v143, v99
	v_fma_f32 v100, v62, v144, v100
	v_fma_f32 v101, v63, v145, v101
	v_fma_f32 v92, v56, v138, v92
	v_fma_f32 v93, v57, v139, v93
	v_fma_f32 v94, v58, v140, v94
	v_fma_f32 v95, v59, v141, v95
	v_fma_f32 v84, v52, v134, v84
	v_fma_f32 v85, v53, v135, v85
	v_fma_f32 v86, v54, v136, v86
	v_fma_f32 v87, v55, v137, v87
	v_fma_f32 v72, v40, v130, v72
	v_fma_f32 v73, v41, v131, v73
	v_fma_f32 v74, v42, v132, v74
	v_fma_f32 v75, v43, v133, v75
	v_add_u32_e32 v170, 0x80000, v168
	global_store_dwordx4 v170, v[98:101], s[28:29]
	global_store_dwordx4 v170, v[92:95], s[28:29] offset:64
	global_store_dwordx4 v170, v[84:87], s[28:29] offset:512
	global_store_dwordx4 v170, v[72:75], s[28:29] offset:576
	v_add_u32_e32 v170, 0xa0000, v168
	global_load_dwordx4 v[60:63], v170, s[30:31]
	global_load_dwordx4 v[56:59], v170, s[30:31] offset:64
	global_load_dwordx4 v[52:55], v170, s[30:31] offset:512
	global_load_dwordx4 v[40:43], v170, s[30:31] offset:576
	s_waitcnt vmcnt(8)
	v_fma_f32 v80, v48, v142, v80
	v_fma_f32 v81, v49, v143, v81
	v_fma_f32 v82, v50, v144, v82
	v_fma_f32 v83, v51, v145, v83
	v_fma_f32 v76, v44, v138, v76
	v_fma_f32 v77, v45, v139, v77
	v_fma_f32 v78, v46, v140, v78
	v_fma_f32 v79, v47, v141, v79
	v_fma_f32 v68, v36, v134, v68
	v_fma_f32 v69, v37, v135, v69
	v_fma_f32 v70, v38, v136, v70
	v_fma_f32 v71, v39, v137, v71
	v_fma_f32 v64, v24, v130, v64
	v_fma_f32 v65, v25, v131, v65
	v_fma_f32 v66, v26, v132, v66
	v_fma_f32 v67, v27, v133, v67
	v_add_u32_e32 v170, 0x90000, v168
	global_store_dwordx4 v170, v[80:83], s[28:29]
	global_store_dwordx4 v170, v[76:79], s[28:29] offset:64
	global_store_dwordx4 v170, v[68:71], s[28:29] offset:512
	global_store_dwordx4 v170, v[64:67], s[28:29] offset:576
	v_add_u32_e32 v170, 0xb0000, v168
	global_load_dwordx4 v[48:51], v170, s[30:31]
	global_load_dwordx4 v[44:47], v170, s[30:31] offset:64
	global_load_dwordx4 v[36:39], v170, s[30:31] offset:512
	global_load_dwordx4 v[24:27], v170, s[30:31] offset:576
	s_waitcnt vmcnt(8)
	v_fma_f32 v60, v32, v142, v60
	v_fma_f32 v61, v33, v143, v61
	v_fma_f32 v62, v34, v144, v62
	v_fma_f32 v63, v35, v145, v63
	v_fma_f32 v56, v28, v138, v56
	v_fma_f32 v57, v29, v139, v57
	v_fma_f32 v58, v30, v140, v58
	v_fma_f32 v59, v31, v141, v59
	v_fma_f32 v52, v20, v134, v52
	v_fma_f32 v53, v21, v135, v53
	v_fma_f32 v54, v22, v136, v54
	v_fma_f32 v55, v23, v137, v55
	v_fma_f32 v40, v8, v130, v40
	v_fma_f32 v41, v9, v131, v41
	v_fma_f32 v42, v10, v132, v42
	v_fma_f32 v43, v11, v133, v43
	v_add_u32_e32 v170, 0xa0000, v168
	global_store_dwordx4 v170, v[60:63], s[28:29]
	global_store_dwordx4 v170, v[56:59], s[28:29] offset:64
	global_store_dwordx4 v170, v[52:55], s[28:29] offset:512
	global_store_dwordx4 v170, v[40:43], s[28:29] offset:576
	s_waitcnt vmcnt(4)
	v_fma_f32 v48, v16, v142, v48
	v_fma_f32 v49, v17, v143, v49
	v_fma_f32 v50, v18, v144, v50
	v_fma_f32 v51, v19, v145, v51
	v_fma_f32 v44, v12, v138, v44
	v_fma_f32 v45, v13, v139, v45
	v_fma_f32 v46, v14, v140, v46
	v_fma_f32 v47, v15, v141, v47
	v_fma_f32 v36, v4, v134, v36
	v_fma_f32 v37, v5, v135, v37
	v_fma_f32 v38, v6, v136, v38
	v_fma_f32 v39, v7, v137, v39
	v_fma_f32 v24, v0, v130, v24
	v_fma_f32 v25, v1, v131, v25
	v_fma_f32 v26, v2, v132, v26
	v_fma_f32 v27, v3, v133, v27
	v_add_u32_e32 v170, 0xb0000, v168
	global_store_dwordx4 v170, v[48:51], s[28:29]
	global_store_dwordx4 v170, v[44:47], s[28:29] offset:64
	global_store_dwordx4 v170, v[36:39], s[28:29] offset:512
	global_store_dwordx4 v170, v[24:27], s[28:29] offset:576
	s_and_b64 vcc, exec, s[2:3]
	s_mov_b64 s[2:3], -1
	s_cbranch_vccnz .LBB0_1966
	s_andn2_b64 vcc, exec, s[10:11]
	s_cbranch_vccnz .LBB0_1965
	s_barrier
	s_branch .LBB0_1965
